# grid barrier: release by announcement count (each XCC leader adds 1 to every XCC word after its writeback, workgroups wait for nx*(round+1)); no returning cross-XCC atomic
# speedup vs baseline: 1.0050x; 1.0050x over previous
; __device__ __forceinline__ unsigned xb_ld(unsigned* p)              { return __hip_atomic_load(p, __ATOMIC_RELAXED, __HIP_MEMORY_SCOPE_AGENT); }
; __device__ __forceinline__ unsigned xb_add(unsigned* p, unsigned v) { return __hip_atomic_fetch_add(p, v, __ATOMIC_RELAXED, __HIP_MEMORY_SCOPE_AGENT); }
; #define XB_SPIN(cond, bar) do { unsigned _sp = 0; while (cond) { __builtin_amdgcn_s_sleep(1); \
;     if ((++_sp & 255u) == 0u) { if (xb_ld(&(bar)[XB_TMO])) break; if (_sp > XB_SPIN_CAP) { atomicAdd(&(bar)[XB_TMO], 1u); break; } } } } while (0)
; __device__ __forceinline__ void xcd_barrier(const XcdBarrier& b) {
;     ...
;         unsigned nloc = b.st[0], nx = b.st[1];
;         if (nloc == 0u) { xcd_barrier_complete(bar, b.x, nloc, nx); b.st[0] = nloc; b.st[1] = nx; }
;         const unsigned old = xb_add(&bar[XB_XSUB(b.x)], 1u);
;         const unsigned gen = old / nloc;
;         if (old + 1u == (gen + 1u) * nloc) {
;             __builtin_amdgcn_fence(__ATOMIC_RELEASE, "agent");
;             asm volatile("s_waitcnt vmcnt(0)" ::: "memory");
;             const unsigned og = xb_add(&bar[XB_TOP], 1u);
;             const unsigned tg = og / nx;
;             if (og + 1u == (tg + 1u) * nx) xb_add(&bar[XB_TOPGEN], 1u);
;             else XB_SPIN(xb_ld(&bar[XB_TOPGEN]) == tg, bar);
;             __builtin_amdgcn_fence(__ATOMIC_ACQUIRE, "agent");
;             xb_add(&bar[XB_XGEN(b.x)], 1u);
;             asm volatile("s_waitcnt vmcnt(0)" ::: "memory");
;         } else {
;             XB_SPIN(xb_ld(&bar[XB_XGEN(b.x)]) == gen, bar);
;             __builtin_amdgcn_fence(__ATOMIC_ACQUIRE, "agent");
;             asm volatile("s_waitcnt vmcnt(0)" ::: "memory");
;         }
.LBB0_1027:
	s_or_b64 exec, exec, s[2:3]
	v_cvt_f32_u32_e32 v5, v3
	s_waitcnt vmcnt(0)
	v_readfirstlane_b32 s2, v4
	v_sub_u32_e32 v4, 0, v3
	v_rcp_iflag_f32_e32 v5, v5
	v_add_u32_e32 v6, s2, v0
	v_mul_f32_e32 v5, 0x4f7ffffe, v5
	v_cvt_u32_f32_e32 v5, v5
	v_mul_lo_u32 v0, v4, v5
	v_mul_hi_u32 v0, v5, v0
	v_add_u32_e32 v0, v5, v0
	v_mul_hi_u32 v0, v6, v0
	v_mul_lo_u32 v4, v0, v3
	v_sub_u32_e32 v4, v6, v4
	v_add_u32_e32 v5, 1, v0
	v_cmp_ge_u32_e32 vcc, v4, v3
	s_nop 1
	v_cndmask_b32_e32 v0, v0, v5, vcc
	v_sub_u32_e32 v5, v4, v3
	v_cndmask_b32_e32 v4, v4, v5, vcc
	v_add_u32_e32 v5, 1, v0
	v_cmp_ge_u32_e32 vcc, v4, v3
	v_add_u32_e32 v4, 1, v6
	s_nop 0
	v_cndmask_b32_e32 v0, v0, v5, vcc
	v_mul_lo_u32 v5, v3, v0
	v_add_u32_e32 v3, v5, v3
	v_add_u32_e32 v7, 1, v0
	v_mul_lo_u32 v7, v7, v2
	v_cmp_ne_u32_e32 vcc, v4, v3
	s_mov_b64 s[2:3], 0
	s_cbranch_vccnz .Lxb_wait
	buffer_wbl2 sc1
	s_waitcnt vmcnt(0) lgkmcnt(0)
	v_readlane_b32 s6, v251, 7
	v_readlane_b32 s7, v251, 8
	v_mov_b32_e32 v8, 1
	s_nop 3
	s_add_u32 s6, s6, 0x2200
	s_addc_u32 s7, s7, 0
	s_nop 0
	global_atomic_add v1, v8, s[6:7]
	global_atomic_add v1, v8, s[6:7] offset:256
	global_atomic_add v1, v8, s[6:7] offset:512
	global_atomic_add v1, v8, s[6:7] offset:768
	global_atomic_add v1, v8, s[6:7] offset:1024
	global_atomic_add v1, v8, s[6:7] offset:1280
	global_atomic_add v1, v8, s[6:7] offset:1536
	global_atomic_add v1, v8, s[6:7] offset:1792
	global_atomic_add v1, v8, s[6:7] offset:2048
	global_atomic_add v1, v8, s[6:7] offset:2304
	global_atomic_add v1, v8, s[6:7] offset:2560
	global_atomic_add v1, v8, s[6:7] offset:2816
	global_atomic_add v1, v8, s[6:7] offset:3072
	global_atomic_add v1, v8, s[6:7] offset:3328
	global_atomic_add v1, v8, s[6:7] offset:3584
	global_atomic_add v1, v8, s[6:7] offset:3840
.Lxb_wait:
	v_readlane_b32 s4, v252, 3
	v_readlane_b32 s5, v252, 4
	s_waitcnt lgkmcnt(0)
	s_nop 3
	buffer_inv sc1
	global_load_dword v2, v1, s[4:5] sc1
	s_waitcnt vmcnt(0)
	v_cmp_gt_u32_e32 vcc, v7, v2
	s_and_saveexec_b64 s[4:5], vcc
	s_cbranch_execz .LBB0_1040
	s_mov_b32 s17, 1
	s_mov_b64 s[6:7], 0
	s_branch .LBB0_1031

; __device__ __forceinline__ unsigned xb_ld(unsigned* p)              { return __hip_atomic_load(p, __ATOMIC_RELAXED, __HIP_MEMORY_SCOPE_AGENT); }
; __device__ __forceinline__ unsigned xb_add(unsigned* p, unsigned v) { return __hip_atomic_fetch_add(p, v, __ATOMIC_RELAXED, __HIP_MEMORY_SCOPE_AGENT); }
; #define XB_SPIN(cond, bar) do { unsigned _sp = 0; while (cond) { __builtin_amdgcn_s_sleep(1); \
;     if ((++_sp & 255u) == 0u) { if (xb_ld(&(bar)[XB_TMO])) break; if (_sp > XB_SPIN_CAP) { atomicAdd(&(bar)[XB_TMO], 1u); break; } } } } while (0)
; __device__ __forceinline__ void xcd_barrier(const XcdBarrier& b) {
;     ...
;             else XB_SPIN(xb_ld(&bar[XB_TOPGEN]) == tg, bar);
;             __builtin_amdgcn_fence(__ATOMIC_ACQUIRE, "agent");
;             xb_add(&bar[XB_XGEN(b.x)], 1u);
;             asm volatile("s_waitcnt vmcnt(0)" ::: "memory");
;         } else {
;             XB_SPIN(xb_ld(&bar[XB_XGEN(b.x)]) == gen, bar);
.LBB0_1033:
	v_readlane_b32 s10, v252, 3
	v_readlane_b32 s11, v252, 4
	s_add_i32 s17, s17, 1
	s_mov_b64 s[12:13], -1
	s_nop 2
	global_load_dword v2, v1, s[10:11] sc1
	s_waitcnt vmcnt(0)
	v_cmp_le_u32_e32 vcc, v7, v2
	s_orn2_b64 s[10:11], vcc, exec
	s_branch .LBB0_1030

; __device__ __forceinline__ unsigned xb_ld(unsigned* p)              { return __hip_atomic_load(p, __ATOMIC_RELAXED, __HIP_MEMORY_SCOPE_AGENT); }
; __device__ __forceinline__ unsigned xb_add(unsigned* p, unsigned v) { return __hip_atomic_fetch_add(p, v, __ATOMIC_RELAXED, __HIP_MEMORY_SCOPE_AGENT); }
; #define XB_SPIN(cond, bar) do { unsigned _sp = 0; while (cond) { __builtin_amdgcn_s_sleep(1); \
;     if ((++_sp & 255u) == 0u) { if (xb_ld(&(bar)[XB_TMO])) break; if (_sp > XB_SPIN_CAP) { atomicAdd(&(bar)[XB_TMO], 1u); break; } } } } while (0)
; __device__ __forceinline__ void xcd_barrier(const XcdBarrier& b) {
;     ...
;         if (old + 1u == (gen + 1u) * nloc) {
;             __builtin_amdgcn_fence(__ATOMIC_RELEASE, "agent");
;             asm volatile("s_waitcnt vmcnt(0)" ::: "memory");
;             const unsigned og = xb_add(&bar[XB_TOP], 1u);
;             const unsigned tg = og / nx;
;             if (og + 1u == (tg + 1u) * nx) xb_add(&bar[XB_TOPGEN], 1u);
;             else XB_SPIN(xb_ld(&bar[XB_TOPGEN]) == tg, bar);
;             __builtin_amdgcn_fence(__ATOMIC_ACQUIRE, "agent");
;             xb_add(&bar[XB_XGEN(b.x)], 1u);
;             asm volatile("s_waitcnt vmcnt(0)" ::: "memory");
.LBB0_1041:
	s_andn2_saveexec_b64 s[2:3], s[2:3]
	s_cbranch_execz .LBB0_1061
.LBB0_1061:
	s_or_b64 exec, exec, s[0:1]
	s_mov_b64 s[0:1], 0
	s_waitcnt lgkmcnt(0)
	s_barrier
